# speedup vs baseline: 1.0221x; 1.0133x over previous
; __device__ __forceinline__ void phase_qknorm(const Params& p) {
;     int tid_o = threadIdx.x; asm volatile("" : "+v"(tid_o));
;     const int lane = tid_o & 63, wid = tid_o >> 6, nw = gridDim.x * 8;
;     bf16_t* proj = (bf16_t*)(p.ws + WS_PROJ);
;     for (int row = blockIdx.x * 8 + wid; row < NTOK; row += nw) {
;         bf16_t* pr = proj + (size_t)row * INP;
; #pragma unroll
;         for (int i = 0; i < 2; ++i) {
;             bf16_t* a = pr + C_DQ + i * 512 + lane * 8;
.LBB0_209:
	s_mov_b64 s[6:7], s[0:1]
	v_mov_b32_e32 v16, v166
	s_nop 0
	v_ashrrev_i32_e32 v10, 6, v16
	v_add_u32_e32 v24, s70, v10
	v_cmp_gt_i32_e32 vcc, s29, v24
	s_and_saveexec_b64 s[14:15], vcc
	s_cbranch_execz .LBB0_208
	v_cmp_lt_i32_e32 vcc, v174, v168
	s_load_dwordx2 s[16:17], s[6:7], 0x80
	s_load_dwordx4 s[36:39], s[6:7], 0x40
	s_load_dwordx2 s[4:5], s[6:7], 0x50
	v_cndmask_b32_e32 v0, v167, v174, vcc
	v_cmp_lt_i32_e32 vcc, v173, v168
	v_lshlrev_b32_e32 v25, 2, v0
	s_waitcnt lgkmcnt(0)
	s_add_u32 s18, s16, 0x3e730000
	v_cndmask_b32_e32 v0, v167, v173, vcc
	v_cmp_lt_i32_e32 vcc, v172, v168
	v_lshlrev_b32_e32 v26, 2, v0
	s_addc_u32 s19, s17, 0
	v_cndmask_b32_e32 v0, v167, v172, vcc
	v_cmp_lt_i32_e32 vcc, v171, v168
	v_lshlrev_b32_e32 v27, 2, v0
	v_and_b32_e32 v11, 63, v16
	v_cndmask_b32_e32 v0, v167, v171, vcc
	v_lshlrev_b32_e32 v28, 2, v0
	v_lshlrev_b32_e32 v0, 3, v16
	v_and_b32_e32 v2, 0x78, v0
	v_lshlrev_b32_e32 v0, 4, v16
	v_and_b32_e32 v31, 48, v0
	v_lshlrev_b32_e32 v0, 2, v2
	v_lshl_add_u64 v[4:5], s[36:37], 0, v[0:1]
	v_lshl_add_u64 v[6:7], s[38:39], 0, v[0:1]
	v_lshlrev_b32_e32 v0, 5, v16
	v_and_b32_e32 v0, 0xe0, v0
	v_lshl_add_u64 v[8:9], s[4:5], 0, v[0:1]
	v_and_b32_e32 v0, 7, v16
	s_add_u32 s20, s16, 0x6330000
	v_mov_b64_e32 v[12:13], s[16:17]
	v_lshl_or_b32 v14, v0, 4, v22
	v_and_b32_e32 v0, 31, v16
	v_cmp_gt_u32_e64 s[6:7], 32, v11
	v_bfe_u32 v29, v16, 4, 1
	v_cmp_gt_u32_e64 s[8:9], 8, v11
	s_addc_u32 s21, s17, 0
	v_bfe_u32 v30, v16, 2, 4
	v_lshl_add_u32 v32, v10, 7, s74
	v_lshlrev_b32_e32 v10, 4, v11
	v_mov_b32_e32 v11, v1
	v_mad_i64_i32 v[12:13], s[4:5], v24, s27, v[12:13]
	v_mov_b32_e32 v15, v1
	v_lshl_or_b32 v16, v0, 4, v23
	v_mov_b32_e32 v17, v1
	s_mov_b64 s[22:23], 0
	global_load_dwordx4 v[92:95], v[4:5], off
	global_load_dwordx4 v[96:99], v[4:5], off offset:16
	global_load_dwordx4 v[100:103], v[6:7], off
	global_load_dwordx4 v[104:107], v[6:7], off offset:16
	global_load_dwordx4 v[108:111], v[8:9], off
	global_load_dwordx4 v[112:115], v[8:9], off offset:16
	s_waitcnt vmcnt(0)
	s_branch .LBB0_212

; __device__ __forceinline__ void phase_qknorm(const Params& p) {
;     ...
;     for (int row = blockIdx.x * 8 + wid; row < NTOK; row += nw) {
;         bf16_t* pr = proj + (size_t)row * INP;
; #pragma unroll
;         for (int i = 0; i < 2; ++i) {
;             bf16_t* a = pr + C_DQ + i * 512 + lane * 8;
;             float f[8]; unpack8(*(const u32x4*)a, f);
;             float ss = 0.f;
; #pragma unroll
;             for (int j = 0; j < 8; ++j) ss += f[j] * f[j];
;             ss += __shfl_xor(ss, 1); ss += __shfl_xor(ss, 2); ss += __shfl_xor(ss, 4); ss += __shfl_xor(ss, 8);
;             const float sc = rsqrtf(ss * (1.0f / 128.0f) + 1e-6f) * 0.08838834764831845f;
; #pragma unroll
;             for (int j = 0; j < 8; ++j) f[j] = f[j] * sc * p.q_norm_g[(lane & 15) * 8 + j];
;             *(u32x4*)a = pack8(f);
;         }
;         {
;             bf16_t* a = pr + C_DK + (lane & 31) * 8;
;             float f[8]; unpack8(*(const u32x4*)a, f);
;             float ss = 0.f;
; #pragma unroll
;             for (int j = 0; j < 8; ++j) ss += f[j] * f[j];
;             ss += __shfl_xor(ss, 1); ss += __shfl_xor(ss, 2); ss += __shfl_xor(ss, 4); ss += __shfl_xor(ss, 8);
;             const float sc = rsqrtf(ss * (1.0f / 128.0f) + 1e-6f);
.LBB0_212:
	v_lshl_add_u64 v[18:19], v[12:13], 0, v[10:11]
	v_add_co_u32_e32 v20, vcc, 0xe732000, v18
	s_waitcnt lgkmcnt(0)
	s_nop 0
	v_addc_co_u32_e32 v21, vcc, 0, v19, vcc
	v_lshl_add_u64 v[88:89], v[12:13], 0, v[16:17]
	v_lshl_add_u64 v[90:91], v[12:13], 0, v[14:15]
	global_load_dwordx4 v[60:63], v[20:21], off
	global_load_dwordx4 v[64:67], v[20:21], off offset:1024
	global_load_dwordx4 v[68:71], v[88:89], off
	global_load_dwordx4 v[72:75], v[20:21], off offset:2560
	global_load_dwordx4 v[76:79], v[90:91], off
	v_mov_b64_e32 v[38:39], v[92:93]
	v_mov_b64_e32 v[40:41], v[94:95]
	v_mov_b64_e32 v[42:43], v[96:97]
	v_mov_b64_e32 v[44:45], v[98:99]
	s_waitcnt vmcnt(4)
	v_mov_b64_e32 v[34:35], v[60:61]
	v_mov_b64_e32 v[36:37], v[62:63]
	v_and_b32_e32 v33, 0xffff0000, v34
	v_lshlrev_b32_e32 v0, 16, v34
	v_and_b32_e32 v34, 0xffff0000, v35
	v_lshlrev_b32_e32 v35, 16, v35
	v_mul_f32_e32 v54, v33, v33
	v_pk_mul_f32 v[48:49], v[34:35], v[34:35]
	v_fmac_f32_e32 v54, v0, v0
	v_and_b32_e32 v46, 0xffff0000, v36
	v_lshlrev_b32_e32 v47, 16, v36
	v_add_f32_e32 v49, v49, v54
	v_pk_mul_f32 v[50:51], v[46:47], v[46:47]
	v_add_f32_e32 v48, v48, v49
	v_and_b32_e32 v36, 0xffff0000, v37
	v_lshlrev_b32_e32 v37, 16, v37
	v_add_f32_e32 v48, v51, v48
	v_pk_mul_f32 v[52:53], v[36:37], v[36:37]
	v_add_f32_e32 v48, v50, v48
	v_add_f32_e32 v48, v53, v48
	v_add_f32_e32 v48, v52, v48
	ds_bpermute_b32 v49, v25, v48
	s_waitcnt lgkmcnt(0)
	v_add_f32_e32 v48, v48, v49
	ds_bpermute_b32 v49, v26, v48
	s_waitcnt lgkmcnt(0)
	v_add_f32_e32 v48, v48, v49
	ds_bpermute_b32 v49, v27, v48
	s_waitcnt lgkmcnt(0)
	v_add_f32_e32 v48, v48, v49
	ds_bpermute_b32 v49, v28, v48
	s_waitcnt lgkmcnt(0)
	v_add_f32_e32 v48, v48, v49
	v_fmamk_f32 v48, v48, 0x3c000000, v3
	v_mul_f32_e32 v49, 0x4b800000, v48
	v_cmp_gt_f32_e32 vcc, s30, v48
	s_nop 1
	v_cndmask_b32_e32 v48, v48, v49, vcc
	v_rsq_f32_e32 v48, v48
	s_nop 0
	v_mul_f32_e32 v49, 0x45800000, v48
	v_cndmask_b32_e32 v48, v48, v49, vcc
	v_mul_f32_e32 v48, 0x3db504f3, v48
	v_mul_f32_e32 v0, v48, v0
	v_mul_f32_e32 v33, v48, v33
	v_mul_f32_e32 v35, v48, v35
	v_mul_f32_e32 v34, v48, v34
	v_mul_f32_e32 v47, v48, v47
	v_mul_f32_e32 v46, v48, v46
	v_mul_f32_e32 v37, v48, v37
	v_mul_f32_e32 v36, v48, v36
	v_mul_f32_e32 v0, v38, v0
	v_mul_f32_e32 v33, v39, v33
	v_mul_f32_e32 v35, v40, v35
	v_mul_f32_e32 v38, v41, v34
	v_mul_f32_e32 v39, v42, v47
	v_mul_f32_e32 v40, v43, v46
	v_mul_f32_e32 v37, v44, v37
	v_mul_f32_e32 v41, v45, v36
	v_cvt_pk_bf16_f32 v34, v0, v33
	v_cvt_pk_bf16_f32 v35, v35, v38
	v_cvt_pk_bf16_f32 v36, v39, v40
	v_cvt_pk_bf16_f32 v37, v37, v41
	s_waitcnt vmcnt(3)
	v_mov_b64_e32 v[38:39], v[64:65]
	v_mov_b64_e32 v[40:41], v[66:67]
	v_and_b32_e32 v33, 0xffff0000, v38
	global_store_dwordx4 v[20:21], v[34:37], off
	s_nop 1
	v_mov_b64_e32 v[34:35], v[92:93]
	v_mov_b64_e32 v[36:37], v[94:95]
	s_nop 0
	v_mov_b64_e32 v[42:43], v[96:97]
	v_mov_b64_e32 v[44:45], v[98:99]
	v_lshlrev_b32_e32 v0, 16, v38
	v_and_b32_e32 v38, 0xffff0000, v39
	v_lshlrev_b32_e32 v39, 16, v39
	v_mul_f32_e32 v54, v33, v33
	v_pk_mul_f32 v[48:49], v[38:39], v[38:39]
	v_fmac_f32_e32 v54, v0, v0
	v_and_b32_e32 v46, 0xffff0000, v40
	v_lshlrev_b32_e32 v47, 16, v40
	v_add_f32_e32 v49, v49, v54
	v_pk_mul_f32 v[50:51], v[46:47], v[46:47]
	v_add_f32_e32 v48, v48, v49
	v_and_b32_e32 v40, 0xffff0000, v41
	v_lshlrev_b32_e32 v41, 16, v41
	v_add_f32_e32 v48, v51, v48
	v_pk_mul_f32 v[52:53], v[40:41], v[40:41]
	v_add_f32_e32 v48, v50, v48
	v_add_f32_e32 v48, v53, v48
	v_add_f32_e32 v48, v52, v48
	ds_bpermute_b32 v49, v25, v48
	s_waitcnt lgkmcnt(0)
	v_add_f32_e32 v48, v48, v49
	ds_bpermute_b32 v49, v26, v48
	s_waitcnt lgkmcnt(0)
	v_add_f32_e32 v48, v48, v49
	ds_bpermute_b32 v49, v27, v48
	s_waitcnt lgkmcnt(0)
	v_add_f32_e32 v48, v48, v49
	ds_bpermute_b32 v49, v28, v48
	s_waitcnt lgkmcnt(0)
	v_add_f32_e32 v48, v48, v49
	v_fmamk_f32 v48, v48, 0x3c000000, v3
	v_mul_f32_e32 v49, 0x4b800000, v48
	v_cmp_gt_f32_e32 vcc, s30, v48
	s_nop 1
	v_cndmask_b32_e32 v48, v48, v49, vcc
	v_rsq_f32_e32 v50, v48
	v_lshl_add_u64 v[48:49], v[12:13], 0, v[16:17]
	v_mul_f32_e32 v51, 0x45800000, v50
	v_cndmask_b32_e32 v50, v50, v51, vcc
	v_mul_f32_e32 v50, 0x3db504f3, v50
	v_mul_f32_e32 v0, v50, v0
	v_mul_f32_e32 v33, v50, v33
	v_mul_f32_e32 v39, v50, v39
	v_mul_f32_e32 v38, v50, v38
	v_mul_f32_e32 v47, v50, v47
	v_mul_f32_e32 v46, v50, v46
	v_mul_f32_e32 v41, v50, v41
	v_mul_f32_e32 v40, v50, v40
	v_mul_f32_e32 v0, v34, v0
	v_mul_f32_e32 v33, v35, v33
	v_mul_f32_e32 v34, v36, v39
	v_mul_f32_e32 v35, v37, v38
	v_mul_f32_e32 v36, v42, v47
	v_mul_f32_e32 v37, v43, v46
	v_mul_f32_e32 v38, v44, v41
	v_mul_f32_e32 v39, v45, v40
	v_cvt_pk_bf16_f32 v42, v0, v33
	v_cvt_pk_bf16_f32 v43, v34, v35
	v_cvt_pk_bf16_f32 v44, v36, v37
	v_cvt_pk_bf16_f32 v45, v38, v39
	s_waitcnt vmcnt(3)
	v_mov_b64_e32 v[36:37], v[68:69]
	v_mov_b64_e32 v[38:39], v[70:71]
	v_and_b32_e32 v33, 0xffff0000, v36
	v_lshlrev_b32_e32 v0, 16, v36
	v_mul_f32_e32 v40, v33, v33
	v_lshlrev_b32_e32 v34, 16, v37
	v_fmac_f32_e32 v40, v0, v0
	v_and_b32_e32 v35, 0xffff0000, v37
	v_fmac_f32_e32 v40, v34, v34
	v_lshlrev_b32_e32 v36, 16, v38
	v_fmac_f32_e32 v40, v35, v35
	v_and_b32_e32 v37, 0xffff0000, v38
	v_fmac_f32_e32 v40, v36, v36
	v_lshlrev_b32_e32 v38, 16, v39
	v_fmac_f32_e32 v40, v37, v37
	v_and_b32_e32 v39, 0xffff0000, v39
	v_fmac_f32_e32 v40, v38, v38
	v_fmac_f32_e32 v40, v39, v39
	ds_bpermute_b32 v41, v25, v40
	global_store_dwordx4 v[20:21], v[42:45], off offset:1024
	v_ashrrev_i32_e32 v20, 13, v24
	s_waitcnt lgkmcnt(0)
	v_add_f32_e32 v40, v40, v41
	ds_bpermute_b32 v41, v26, v40
	s_waitcnt lgkmcnt(0)
	v_add_f32_e32 v40, v40, v41
	ds_bpermute_b32 v41, v27, v40
	s_waitcnt lgkmcnt(0)
	v_add_f32_e32 v40, v40, v41
	ds_bpermute_b32 v41, v28, v40
	s_and_saveexec_b64 s[24:25], s[6:7]
	s_cbranch_execz .LBB0_214
; __device__ __forceinline__ void phase_qknorm(const Params& p) {
;     ...
;             const float sc = rsqrtf(ss * (1.0f / 128.0f) + 1e-6f);
; #pragma unroll
;             for (int j = 0; j < 8; ++j) f[j] = f[j] * sc * p.k_norm_g[(lane & 15) * 8 + j];
;             const int bb = row >> 13, pos = row & (SEQ - 1), gg = (lane >> 4) & 1;
;             const size_t co = ((size_t)(bb * 2 + gg) * SEQ + pos) * 128 + (lane & 15) * 8;
;             if (lane < 32) { *(u32x4*)((bf16_t*)(p.ws + WS_KC) + co) = pack8(f); *(u32x4*)((bf16_t*)(p.ws + WS_VC) + co) = *(const u32x4*)(pr + C_DV + lane * 8); }
;         }
;         {
;             bf16_t* a = pr + C_IK + (lane & 7) * 8;
;             float f[8]; unpack8(*(const u32x4*)a, f);
;             float ss = 0.f;
; #pragma unroll
;             for (int j = 0; j < 8; ++j) ss += f[j] * f[j];
;             ss += __shfl_xor(ss, 1); ss += __shfl_xor(ss, 2); ss += __shfl_xor(ss, 4);
;             const float sc = rsqrtf(ss * (1.0f / 64.0f) + 1e-6f);
; #pragma unroll
;             for (int j = 0; j < 8; ++j) f[j] = f[j] * sc * p.idx_k_norm_g[(lane & 7) * 8 + j];
;             if (lane < 8) { const int pos = row & (SEQ - 1), bb = row >> 13;
;                 *(u32x4*)((bf16_t*)(p.ws + WS_IKC) + (size_t)bb * SEQ * 64 + ((size_t)((pos >> 4) * 2 + (lane >> 2)) * 64 + (lane & 3) * 16 + (pos & 15)) * 8) = pack8(f); }
	v_mov_b64_e32 v[42:43], v[104:105]
	v_mov_b64_e32 v[44:45], v[106:107]
	v_mov_b64_e32 v[46:47], v[100:101]
	v_mov_b64_e32 v[48:49], v[102:103]
	s_waitcnt lgkmcnt(0)
	v_add_f32_e32 v21, v40, v41
	v_fmamk_f32 v21, v21, 0x3c000000, v3
	v_mul_f32_e32 v50, 0x4b800000, v21
	v_cmp_gt_f32_e64 s[10:11], s30, v21
	v_lshl_or_b32 v40, v20, 1, v29
	v_ashrrev_i32_e32 v41, 31, v40
	v_cndmask_b32_e64 v21, v21, v50, s[10:11]
	v_rsq_f32_e32 v21, v21
	v_lshlrev_b64 v[40:41], 20, v[40:41]
	v_and_or_b32 v40, v32, s31, v40
	v_or_b32_e32 v40, v40, v2
	v_mul_f32_e32 v52, 0x45800000, v21
	v_cndmask_b32_e64 v21, v21, v52, s[10:11]
	v_lshlrev_b64 v[40:41], 1, v[40:41]
	v_mul_f32_e32 v35, v21, v35
	v_mul_f32_e32 v36, v21, v36
	v_mul_f32_e32 v37, v21, v37
	v_add_co_u32_e32 v18, vcc, 0xe732000, v18
	v_lshl_add_u64 v[50:51], s[16:17], 0, v[40:41]
	v_mul_f32_e32 v39, v21, v39
	v_mul_f32_e32 v0, v21, v0
	v_mul_f32_e32 v33, v21, v33
	v_mul_f32_e32 v34, v21, v34
	v_mul_f32_e32 v21, v21, v38
	v_addc_co_u32_e32 v19, vcc, 0, v19, vcc
	v_mul_f32_e32 v36, v36, v42
	v_mul_f32_e32 v35, v35, v49
	v_mul_f32_e32 v37, v37, v43
	v_mul_f32_e32 v38, v39, v45
	v_mul_f32_e32 v0, v0, v46
	v_mul_f32_e32 v33, v33, v47
	v_mul_f32_e32 v39, v34, v48
	v_mul_f32_e32 v21, v21, v44
	v_cvt_pk_bf16_f32 v34, v0, v33
	v_cvt_pk_bf16_f32 v35, v39, v35
	v_cvt_pk_bf16_f32 v36, v36, v37
	v_cvt_pk_bf16_f32 v37, v21, v38
	global_store_dwordx4 v[50:51], v[34:37], off
	v_lshl_add_u64 v[18:19], s[18:19], 0, v[40:41]
	s_waitcnt vmcnt(4)
	v_mov_b64_e32 v[34:35], v[72:73]
	v_mov_b64_e32 v[36:37], v[74:75]
	global_store_dwordx4 v[18:19], v[34:37], off
.LBB0_214:
	s_or_b64 exec, exec, s[24:25]
	v_lshl_add_u64 v[18:19], v[12:13], 0, v[14:15]
	s_waitcnt vmcnt(4)
	v_mov_b64_e32 v[36:37], v[76:77]
	v_mov_b64_e32 v[38:39], v[78:79]
	v_and_b32_e32 v19, 0xffff0000, v36
	v_lshlrev_b32_e32 v18, 16, v36
	v_mul_f32_e32 v0, v19, v19
	v_lshlrev_b32_e32 v33, 16, v37
	v_fmac_f32_e32 v0, v18, v18
	v_and_b32_e32 v34, 0xffff0000, v37
	v_fmac_f32_e32 v0, v33, v33
	v_lshlrev_b32_e32 v35, 16, v38
	v_fmac_f32_e32 v0, v34, v34
	v_and_b32_e32 v36, 0xffff0000, v38
	v_fmac_f32_e32 v0, v35, v35
	v_lshlrev_b32_e32 v37, 16, v39
	v_fmac_f32_e32 v0, v36, v36
	v_and_b32_e32 v38, 0xffff0000, v39
	v_fmac_f32_e32 v0, v37, v37
	v_fmac_f32_e32 v0, v38, v38
	ds_bpermute_b32 v21, v25, v0
	s_waitcnt lgkmcnt(0)
	v_add_f32_e32 v0, v0, v21
	ds_bpermute_b32 v21, v26, v0
	s_waitcnt lgkmcnt(0)
	v_add_f32_e32 v0, v0, v21
	ds_bpermute_b32 v21, v27, v0
	s_and_saveexec_b64 s[10:11], s[8:9]
	s_cbranch_execz .LBB0_211
	v_mov_b64_e32 v[40:41], v[112:113]
	v_mov_b64_e32 v[42:43], v[114:115]
	v_mov_b64_e32 v[44:45], v[108:109]
	v_mov_b64_e32 v[46:47], v[110:111]
	s_waitcnt lgkmcnt(0)
	v_add_f32_e32 v0, v0, v21
	v_fmamk_f32 v0, v0, 0x3c800000, v3
	v_ashrrev_i32_e32 v21, 31, v20
	v_mul_f32_e32 v51, 0x4b800000, v0
	v_cmp_gt_f32_e32 vcc, s30, v0
	v_lshlrev_b64 v[20:21], 20, v[20:21]
	v_lshl_add_u64 v[48:49], s[20:21], 0, v[20:21]
	v_cndmask_b32_e32 v0, v0, v51, vcc
	v_rsq_f32_e32 v20, v0
	v_lshrrev_b32_e32 v39, 3, v24
	v_and_or_b32 v39, v39, s34, v30
	v_and_b32_e32 v50, 15, v24
	v_mul_f32_e32 v21, 0x45800000, v20
	v_lshlrev_b32_e32 v0, 6, v39
	v_cndmask_b32_e32 v20, v20, v21, vcc
	v_or3_b32 v0, v0, v31, v50
	v_mul_f32_e32 v18, v20, v18
	v_mul_f32_e32 v19, v20, v19
	v_mul_f32_e32 v34, v20, v34
	v_mul_f32_e32 v35, v20, v35
	v_lshlrev_b32_e32 v0, 4, v0
	v_mul_f32_e32 v21, v20, v38
	v_mul_f32_e32 v33, v20, v33
	v_mul_f32_e32 v36, v20, v36
	v_mul_f32_e32 v20, v20, v37
	v_mul_f32_e32 v35, v35, v40
	v_mul_f32_e32 v18, v18, v44
	v_mul_f32_e32 v19, v19, v45
	v_mul_f32_e32 v34, v34, v47
	v_mul_f32_e32 v21, v21, v43
	v_mul_f32_e32 v33, v33, v46
	v_mul_f32_e32 v36, v36, v41
	v_mul_f32_e32 v37, v20, v42
	v_cvt_pk_bf16_f32 v18, v18, v19
	v_cvt_pk_bf16_f32 v19, v33, v34
	v_cvt_pk_bf16_f32 v20, v35, v36
	v_lshl_add_u64 v[34:35], v[48:49], 0, v[0:1]
	v_cvt_pk_bf16_f32 v21, v37, v21
	global_store_dwordx4 v[34:35], v[18:21], off
	s_branch .LBB0_211
